# P3 row split between the SSM-GEMM workgroups and the row-only workgroups moved from 4864 to 3072 rows (the row loop is faster now)
# speedup vs baseline: 1.0052x; 1.0015x over previous
.LBB0_393:
	s_and_b64 vcc, exec, s[6:7]
	s_cbranch_vccz .LBB0_416
	v_mov_b32_e32 v4, v234
	s_lshl_b64 s[4:5], s[82:83], 3
	v_readfirstlane_b32 s0, v4
	s_ashr_i32 s1, s0, 6
	v_readlane_b32 s6, v255, 3
	v_readlane_b32 s7, v255, 4
	s_add_u32 s12, s6, s4
	s_addc_u32 s13, s7, s5
	s_load_dwordx8 s[4:11], s[12:13], 0x38
	v_and_b32_e32 v2, 63, v4
	v_readlane_b32 s14, v255, 26
	s_lshl_b32 s0, s59, 3
	s_mov_b32 s52, s34
	v_lshl_or_b32 v6, s14, 6, v2
	s_waitcnt lgkmcnt(0)
	v_ashrrev_i32_e32 v7, 31, v6
	v_lshlrev_b64 v[6:7], 2, v[6:7]
	s_waitcnt lgkmcnt(0)
	v_lshl_add_u64 v[8:9], s[4:5], 0, v[6:7]
	global_load_dword v3, v[8:9], off
	v_lshl_add_u64 v[8:9], s[6:7], 0, v[6:7]
	global_load_dword v5, v[8:9], off
	v_lshlrev_b32_e32 v9, 2, v2
	v_xor_b32_e32 v1, 4, v9
	v_xor_b32_e32 v36, 8, v9
	v_xor_b32_e32 v37, 16, v9
	v_xor_b32_e32 v38, 32, v9
	v_xor_b32_e32 v10, 64, v9
	v_xor_b32_e32 v11, 0x80, v9
	s_and_b32 s4, s0, 0x3f8
	s_cmpk_gt_i32 s59, 0x7f
	s_cselect_b32 s5, 0xc00, 0
	s_movk_i32 s0, 0xc00
	s_cselect_b32 s0, 0x4000, s0
	s_add_i32 s4, s5, s4
	s_add_i32 s6, s4, s1
	s_cmp_ge_i32 s6, s0
	v_readlane_b32 s15, v255, 27
	s_waitcnt vmcnt(0)
	v_mul_f32_e32 v8, v3, v5
	ds_bpermute_b32 v8, v1, v8
	s_waitcnt lgkmcnt(0)
	v_fmac_f32_e32 v8, v3, v5
	ds_bpermute_b32 v3, v36, v8
	s_waitcnt lgkmcnt(0)
	v_add_f32_e32 v3, v8, v3
	v_lshl_add_u64 v[8:9], s[8:9], 0, v[6:7]
	v_lshl_add_u64 v[6:7], s[10:11], 0, v[6:7]
	global_load_dword v8, v[8:9], off
	ds_bpermute_b32 v5, v37, v3
	global_load_dword v6, v[6:7], off
	s_waitcnt lgkmcnt(0)
	v_add_f32_e32 v3, v3, v5
	ds_bpermute_b32 v5, v38, v3
	s_waitcnt lgkmcnt(0)
	v_add_f32_e32 v3, v3, v5
	ds_bpermute_b32 v5, v10, v3
	s_waitcnt lgkmcnt(0)
	v_add_f32_e32 v3, v3, v5
	ds_bpermute_b32 v5, v11, v3
	s_waitcnt vmcnt(0)
	v_mul_f32_e32 v7, v8, v6
	ds_bpermute_b32 v7, v1, v7
	s_waitcnt lgkmcnt(0)
	v_fmac_f32_e32 v7, v8, v6
	ds_bpermute_b32 v6, v36, v7
	s_waitcnt lgkmcnt(0)
	v_add_f32_e32 v6, v7, v6
	ds_bpermute_b32 v7, v37, v6
	s_waitcnt lgkmcnt(0)
	v_add_f32_e32 v6, v6, v7
	ds_bpermute_b32 v7, v38, v6
	s_waitcnt lgkmcnt(0)
	v_add_f32_e32 v6, v6, v7
	ds_bpermute_b32 v7, v10, v6
	s_waitcnt lgkmcnt(0)
	v_add_f32_e32 v6, v6, v7
	ds_bpermute_b32 v7, v11, v6
	s_cbranch_scc1 .LBB0_397
	v_readlane_b32 s8, v255, 26
	s_load_dwordx2 s[4:5], s[12:13], 0x58
	v_readlane_b32 s9, v255, 27
	v_cvt_f32_i32_e32 v8, s8
	s_lshl_b32 s8, s8, 7
	s_ashr_i32 s9, s8, 31
	s_lshl_b64 s[8:9], s[8:9], 2
	v_mul_f32_e32 v8, 0xbe99999a, v8
	v_mul_f32_e32 v9, 0x3fb8aa3b, v8
	v_fma_f32 v10, v8, s28, -v9
	v_rndne_f32_e32 v11, v9
	v_fmac_f32_e32 v10, 0x32a5705f, v8
	v_sub_f32_e32 v9, v9, v11
	v_add_f32_e32 v9, v9, v10
	v_exp_f32_e32 v9, v9
	v_cvt_i32_f32_e32 v10, v11
	v_cmp_ngt_f32_e32 vcc, s76, v8
	s_waitcnt lgkmcnt(0)
	s_add_u32 s4, s4, s8
	s_addc_u32 s5, s5, s9
	v_ldexp_f32 v9, v9, v10
	v_cndmask_b32_e32 v9, 0, v9, vcc
	v_cmp_nlt_f32_e32 vcc, s30, v8
	s_ashr_i32 s7, s6, 31
	v_readlane_b32 s8, v255, 5
	v_cndmask_b32_e32 v8, v235, v9, vcc
	v_mov_b32_e32 v9, 0x3f4ccccd
	v_fmamk_f32 v24, v8, 0xbf19999a, v9
	v_lshlrev_b32_e32 v8, 5, v4
	v_and_b32_e32 v12, 0x1e0, v8
	global_load_dwordx4 v[8:11], v12, s[4:5] offset:16
	s_nop 0
	global_load_dwordx4 v[12:15], v12, s[4:5]
	v_sub_f32_e32 v22, 1.0, v24
	v_lshlrev_b32_e32 v4, 4, v4
	s_lshl_b64 s[4:5], s[6:7], 10
	v_readlane_b32 s9, v255, 6
	s_mul_hi_i32 s1, s6, 0xc00
	s_waitcnt vmcnt(1)
	v_pk_mul_f32 v[20:21], v[22:23], v[10:11] op_sel_hi:[0,1]
	s_waitcnt vmcnt(0)
	v_pk_mul_f32 v[16:17], v[22:23], v[14:15] op_sel_hi:[0,1]
	v_pk_mul_f32 v[18:19], v[22:23], v[12:13] op_sel_hi:[0,1]
	v_pk_mul_f32 v[22:23], v[22:23], v[8:9] op_sel_hi:[0,1]
	v_lshrrev_b32_e32 v8, 4, v2
	v_add_f32_e32 v2, v3, v5
	v_mul_f32_e32 v3, 0x3fb8aa3b, v2
	v_fma_f32 v5, v2, s28, -v3
	v_rndne_f32_e32 v9, v3
	v_fmac_f32_e32 v5, 0x32a5705f, v2
	v_sub_f32_e32 v3, v3, v9
	v_add_f32_e32 v3, v3, v5
	v_exp_f32_e32 v3, v3
	v_cvt_i32_f32_e32 v5, v9
	v_cmp_ngt_f32_e32 vcc, s76, v2
	v_ldexp_f32 v3, v3, v5
	s_nop 0
	v_cndmask_b32_e32 v3, 0, v3, vcc
	v_cmp_nlt_f32_e32 vcc, s30, v2
	s_nop 1
	v_cndmask_b32_e32 v2, v235, v3, vcc
	v_add_f32_e32 v3, v6, v7
	v_mul_f32_e32 v5, 0x3fb8aa3b, v3
	v_fma_f32 v6, v3, s28, -v5
	v_rndne_f32_e32 v7, v5
	v_fmac_f32_e32 v6, 0x32a5705f, v3
	v_sub_f32_e32 v5, v5, v7
	v_add_f32_e32 v5, v5, v6
	v_exp_f32_e32 v5, v5
	v_cvt_i32_f32_e32 v6, v7
	v_cmp_ngt_f32_e32 vcc, s76, v3
	v_and_b32_e32 v7, 0xf0, v4
	v_ldexp_f32 v5, v5, v6
	v_cndmask_b32_e32 v5, 0, v5, vcc
	v_cmp_nlt_f32_e32 vcc, s30, v3
	v_lshlrev_b32_e32 v6, 8, v8
	v_or3_b32 v4, s4, v6, v7
	v_cndmask_b32_e32 v3, v235, v5, vcc
	v_mov_b32_e32 v5, s5
	s_lshl_b64 s[4:5], s[6:7], 4
	s_add_u32 s4, s8, s4
	v_lshl_add_u64 v[26:27], s[8:9], 0, v[4:5]
	v_lshlrev_b32_e32 v4, 2, v8
	v_mov_b32_e32 v5, v0
	s_addc_u32 s5, s9, s5
	v_lshl_add_u64 v[28:29], s[4:5], 0, v[4:5]
	s_mul_i32 s4, s6, 0xc00
	v_or3_b32 v4, s4, v6, v7
	v_mov_b32_e32 v5, s1
	v_sub_f32_e32 v2, v2, v3
	v_lshl_add_u64 v[30:31], s[8:9], 0, v[4:5]
	s_lshl_b64 s[4:5], s[6:7], 11
	v_lshlrev_b32_e32 v4, 9, v8
	v_add_f32_e32 v24, v24, v2
	v_or3_b32 v4, s4, v4, v7
	v_mov_b32_e32 v5, s5
	v_mov_b32_e32 v25, v24
	v_mov_b32_e32 v2, v24
	v_mov_b32_e32 v3, v24
	v_lshl_add_u64 v[32:33], s[8:9], 0, v[4:5]
